# sample memory attention: the pair-A gate load is issued before pair-B's 16 value loads and waited with vmcnt(16) instead of vmcnt(0), so the output-writing waves no longer wait for pair B's whole stre
# speedup vs baseline: 1.0058x; 1.0058x over previous
.LBB0_590:
	s_or_b64 exec, exec, s[44:45]
	v_lshl_add_u64 v[32:33], v[136:137], 2, s[42:43]
	v_lshl_add_u64 v[32:33], v[32:33], 0, v[2:3]
	s_waitcnt lgkmcnt(3)
	v_add_co_u32_e32 v34, vcc, 0x1000, v32
	s_waitcnt lgkmcnt(2)
	s_nop 0
	v_addc_co_u32_e32 v35, vcc, 0, v33, vcc
	v_readlane_b32 s48, v254, 39
	v_readlane_b32 s49, v254, 40
	s_nop 1
	v_ashrrev_i32_e32 v151, 31, v132
	v_mov_b32_e32 v150, v132
	v_lshlrev_b64 v[150:151], 1, v[150:151]
	v_lshl_add_u64 v[150:151], s[48:49], 0, v[150:151]
	global_load_ushort v152, v[150:151], off
	global_load_dwordx4 v[104:107], v[32:33], off nt
	global_load_dwordx4 v[100:103], v[34:35], off nt
	v_add_co_u32_e32 v34, vcc, 0x2000, v32
	s_nop 1
	v_addc_co_u32_e32 v35, vcc, 0, v33, vcc
	v_add_co_u32_e32 v44, vcc, 0x3000, v32
	s_nop 1
	v_addc_co_u32_e32 v45, vcc, 0, v33, vcc
	global_load_dwordx4 v[112:115], v[34:35], off nt
	global_load_dwordx4 v[108:111], v[44:45], off nt
	v_add_co_u32_e32 v34, vcc, s90, v32
	s_nop 1
	v_addc_co_u32_e32 v35, vcc, 0, v33, vcc
	v_add_co_u32_e32 v44, vcc, 0x5000, v32
	s_nop 1
	v_addc_co_u32_e32 v45, vcc, 0, v33, vcc
	global_load_dwordx4 v[120:123], v[34:35], off nt
	global_load_dwordx4 v[116:119], v[44:45], off nt
	v_add_co_u32_e32 v34, vcc, s33, v32
	s_nop 1
	v_addc_co_u32_e32 v35, vcc, 0, v33, vcc
	v_add_co_u32_e32 v44, vcc, 0x7000, v32
	s_nop 1
	v_addc_co_u32_e32 v45, vcc, 0, v33, vcc
	global_load_dwordx4 v[128:131], v[34:35], off nt
	global_load_dwordx4 v[124:127], v[44:45], off nt
	v_add_co_u32_e32 v34, vcc, s92, v32
	s_nop 1
	v_addc_co_u32_e32 v35, vcc, 0, v33, vcc
	v_add_co_u32_e32 v44, vcc, 0x9000, v32
	s_nop 1
	v_addc_co_u32_e32 v45, vcc, 0, v33, vcc
	global_load_dwordx4 v[96:99], v[34:35], off nt
	global_load_dwordx4 v[92:95], v[44:45], off nt
	v_add_co_u32_e32 v34, vcc, s93, v32
	s_nop 1
	v_addc_co_u32_e32 v35, vcc, 0, v33, vcc
	v_add_co_u32_e32 v44, vcc, 0xb000, v32
	s_nop 1
	v_addc_co_u32_e32 v45, vcc, 0, v33, vcc
	global_load_dwordx4 v[88:91], v[34:35], off nt
	global_load_dwordx4 v[84:87], v[44:45], off nt
	v_add_co_u32_e32 v34, vcc, s6, v32
	s_nop 1
	v_addc_co_u32_e32 v35, vcc, 0, v33, vcc
	v_add_co_u32_e32 v44, vcc, 0xd000, v32
	s_nop 1
	v_addc_co_u32_e32 v45, vcc, 0, v33, vcc
	global_load_dwordx4 v[64:67], v[34:35], off nt
	global_load_dwordx4 v[56:59], v[44:45], off nt
	v_add_co_u32_e32 v34, vcc, 0xe000, v32
	s_nop 1
	v_addc_co_u32_e32 v35, vcc, 0, v33, vcc
	v_add_co_u32_e32 v32, vcc, 0xf000, v32
	s_nop 1
	v_addc_co_u32_e32 v33, vcc, 0, v33, vcc
	s_waitcnt lgkmcnt(0)
	global_load_dwordx4 v[44:47], v[34:35], off nt
	s_nop 0
	global_load_dwordx4 v[32:35], v[32:33], off nt
	s_movk_i32 s1, 0x80
	v_cmp_gt_i32_e64 s[42:43], s1, v132
	v_ashrrev_i32_e32 v133, 31, v132
	v_lshl_add_u32 v2, v132, 2, 0
	s_barrier
	s_and_saveexec_b64 s[44:45], s[42:43]
	s_cbranch_execz .LBB0_592
	ds_read2st64_b32 v[136:137], v2 offset0:8 offset1:10
	v_readlane_b32 s46, v254, 39
	v_readlane_b32 s47, v254, 40
	s_waitcnt lgkmcnt(0)
	v_add_f32_e32 v136, 0, v136
	v_add_f32_e32 v147, v136, v137
	ds_read2st64_b32 v[136:137], v2 offset0:12 offset1:14
	s_waitcnt lgkmcnt(0)
	v_add_f32_e32 v136, v147, v136
	v_add_f32_e32 v147, v136, v137
	ds_read2st64_b32 v[136:137], v2 offset0:16 offset1:18
	s_waitcnt lgkmcnt(0)
	v_add_f32_e32 v136, v147, v136
	v_add_f32_e32 v147, v136, v137
	ds_read2st64_b32 v[136:137], v2 offset0:20 offset1:22
	s_waitcnt lgkmcnt(0)
	v_add_f32_e32 v136, v147, v136
	v_add_f32_e32 v147, v136, v137
	v_lshlrev_b64 v[136:137], 1, v[132:133]
	v_readlane_b32 s46, v255, 4
	v_readlane_b32 s47, v255, 5
	s_waitcnt vmcnt(16)
	v_lshlrev_b32_e32 v148, 16, v152
	v_mul_f32_e32 v147, v147, v148
	v_cvt_pk_bf16_f32 v147, v147, s0
	v_lshl_add_u64 v[136:137], s[46:47], 0, v[136:137]
	global_store_short v[136:137], v147, off sc1

.LBB0_717:
	s_or_b64 exec, exec, s[44:45]
	v_lshl_add_u64 v[40:41], v[136:137], 2, s[46:47]
	v_lshl_add_u64 v[40:41], v[40:41], 0, v[2:3]
	s_waitcnt lgkmcnt(3)
	v_add_co_u32_e32 v42, vcc, 0x1000, v40
	s_waitcnt lgkmcnt(2)
	s_nop 0
	v_addc_co_u32_e32 v43, vcc, 0, v41, vcc
	v_ashrrev_i32_e32 v151, 31, v132
	v_mov_b32_e32 v150, v132
	v_lshlrev_b64 v[150:151], 1, v[150:151]
	v_lshl_add_u64 v[150:151], s[68:69], 0, v[150:151]
	global_load_ushort v152, v[150:151], off
	global_load_dwordx4 v[104:107], v[40:41], off nt
	global_load_dwordx4 v[100:103], v[42:43], off nt
	v_add_co_u32_e32 v42, vcc, 0x2000, v40
	s_nop 1
	v_addc_co_u32_e32 v43, vcc, 0, v41, vcc
	v_add_co_u32_e32 v52, vcc, 0x3000, v40
	s_nop 1
	v_addc_co_u32_e32 v53, vcc, 0, v41, vcc
	global_load_dwordx4 v[112:115], v[42:43], off nt
	global_load_dwordx4 v[108:111], v[52:53], off nt
	v_add_co_u32_e32 v42, vcc, s14, v40
	s_nop 1
	v_addc_co_u32_e32 v43, vcc, 0, v41, vcc
	v_add_co_u32_e32 v52, vcc, 0x5000, v40
	s_nop 1
	v_addc_co_u32_e32 v53, vcc, 0, v41, vcc
	global_load_dwordx4 v[120:123], v[42:43], off nt
	global_load_dwordx4 v[116:119], v[52:53], off nt
	v_add_co_u32_e32 v42, vcc, s33, v40
	s_nop 1
	v_addc_co_u32_e32 v43, vcc, 0, v41, vcc
	v_add_co_u32_e32 v52, vcc, 0x7000, v40
	s_nop 1
	v_addc_co_u32_e32 v53, vcc, 0, v41, vcc
	global_load_dwordx4 v[128:131], v[42:43], off nt
	global_load_dwordx4 v[124:127], v[52:53], off nt
	v_add_co_u32_e32 v42, vcc, s24, v40
	s_nop 1
	v_addc_co_u32_e32 v43, vcc, 0, v41, vcc
	v_add_co_u32_e32 v52, vcc, 0x9000, v40
	s_nop 1
	v_addc_co_u32_e32 v53, vcc, 0, v41, vcc
	global_load_dwordx4 v[96:99], v[42:43], off nt
	global_load_dwordx4 v[92:95], v[52:53], off nt
	v_add_co_u32_e32 v42, vcc, s20, v40
	s_nop 1
	v_addc_co_u32_e32 v43, vcc, 0, v41, vcc
	v_add_co_u32_e32 v52, vcc, 0xb000, v40
	s_nop 1
	v_addc_co_u32_e32 v53, vcc, 0, v41, vcc
	global_load_dwordx4 v[88:91], v[42:43], off nt
	global_load_dwordx4 v[84:87], v[52:53], off nt
	v_add_co_u32_e32 v42, vcc, s6, v40
	s_nop 1
	v_addc_co_u32_e32 v43, vcc, 0, v41, vcc
	v_add_co_u32_e32 v52, vcc, 0xd000, v40
	s_nop 1
	v_addc_co_u32_e32 v53, vcc, 0, v41, vcc
	global_load_dwordx4 v[72:75], v[42:43], off nt
	global_load_dwordx4 v[64:67], v[52:53], off nt
	v_add_co_u32_e32 v42, vcc, 0xe000, v40
	s_nop 1
	v_addc_co_u32_e32 v43, vcc, 0, v41, vcc
	v_add_co_u32_e32 v40, vcc, 0xf000, v40
	s_nop 1
	v_addc_co_u32_e32 v41, vcc, 0, v41, vcc
	s_waitcnt lgkmcnt(0)
	global_load_dwordx4 v[52:55], v[42:43], off nt
	s_nop 0
	global_load_dwordx4 v[40:43], v[40:41], off nt
	s_movk_i32 s14, 0x80
	v_cmp_gt_i32_e64 s[44:45], s14, v132
	v_ashrrev_i32_e32 v133, 31, v132
	v_lshl_add_u32 v2, v132, 2, 0
	s_barrier
	s_and_saveexec_b64 s[46:47], s[44:45]
	s_cbranch_execz .LBB0_719
	ds_read2st64_b32 v[136:137], v2 offset0:8 offset1:10
	s_waitcnt lgkmcnt(0)
	v_add_f32_e32 v136, 0, v136
	v_add_f32_e32 v141, v136, v137
	ds_read2st64_b32 v[136:137], v2 offset0:12 offset1:14
	s_waitcnt lgkmcnt(0)
	v_add_f32_e32 v136, v141, v136
	v_add_f32_e32 v141, v136, v137
	ds_read2st64_b32 v[136:137], v2 offset0:16 offset1:18
	s_waitcnt lgkmcnt(0)
	v_add_f32_e32 v136, v141, v136
	v_add_f32_e32 v141, v136, v137
	ds_read2st64_b32 v[136:137], v2 offset0:20 offset1:22
	s_waitcnt lgkmcnt(0)
	v_add_f32_e32 v136, v141, v136
	v_add_f32_e32 v141, v136, v137
	v_lshlrev_b64 v[136:137], 1, v[132:133]
	v_lshl_add_u64 v[136:137], s[72:73], 0, v[136:137]
	s_waitcnt vmcnt(16)
	v_lshlrev_b32_e32 v142, 16, v152
	v_mul_f32_e32 v141, v141, v142
	v_cvt_pk_bf16_f32 v141, v141, s0
	global_store_short v[136:137], v141, off sc1
